# kv-split attention: waves 0-3 issue every K/V LDS-DMA piece (waves 4-7 none), next step's first score MFMA issued before the barrier/back edge
# speedup vs baseline: 1.0424x; 1.0001x over previous
; #define WAIT_BAR(N) asm volatile("s_waitcnt vmcnt(" #N ") lgkmcnt(0)\n\ts_barrier":::"memory")
;   #define DMA_K(t,slot) glds16(ksrc+(long)(t)*KVBLK*PITCH,(unsigned)__builtin_amdgcn_readfirstlane(kdst+(slot)))
; template<int MODE,int THRL,bool NOMAX> __device__ __forceinline__ void attn_unit(const bf16*Qs,const bf16*__restrict__ Ks,const bf16*__restrict__ Vs,bf16*Os,int S,int q0,float sink2,float slope2,float*ssq,char*shm,int tid_in){
;     ...
;   const bf16*Qw=Qs+(long)(q0+wid*QBLK)*PITCH;
;   const bf16*Kh=Ks+(long)kt0*KVBLK*PITCH,*Vh=Vs+(long)kt0*KVBLK*PITCH;
;   const unsigned lds0=(unsigned)(uintptr_t)shm;
;   float*wsf=(float*)(shm+LDS_WS)+wid*64;
;   const bf16*ksrc=Kh+(long)lane*PITCH+wid*8;
;   const bf16*vsrc=Vh+(long)(16*(wid&3)+(lane>>2))*PITCH+(wid>>2)*32+(lane&3)*8;
;   const unsigned kdst=lds0+LDS_K+wid*1024, vdst=lds0+LDS_V+wid*1024;
;     ...
;   const int vb0=(int)(lds0+LDS_V)+((lane>>4)&1)*32+(lane&3)*8+(4*hi+((lane&15)>>2))*64;
;   const char*Kbase=shm+LDS_K; bf16x8 kf[8];
;   const lds_cptr shm3=(lds_cptr)shm; const lds_cptr kp0=shm3+LDS_K+hi*1024+r32*16; const lds_cptr vp0=shm3+LDS_V+((lane>>4)&1)*32+(lane&3)*8+(4*hi+((lane&15)>>2))*64;
;   const int NT=kend-kt0;
;   DMA_K(0,0);DMA_V(0,0);DMA_K(1,SLOTB);
;   bf16x8 qr[4];
;   #pragma unroll
;   for(int d0=0;d0<4;++d0)qr[d0]=*reinterpret_cast<const bf16x8*>(&Qw[(long)r32*PITCH+d0*16+hi*8]);
;   float mhat=0.f,l_reg=0.f;f32x16 o[2];o[0]=f32x16{};o[1]=f32x16{};f32x16 negm=f32x16{};
;   if(MODE==1){ mhat=sink2; l_reg=(hi==0)?1.f:0.f;
;     #pragma unroll
;     for(int r=0;r<16;++r)negm[r]=-sink2; }
;   if(!NOMAX)asm volatile("":"+v"(negm));
;   f32x16 lsum=f32x16{}; bf16x8 onesv;
;   #pragma unroll
;   for(int i_=0;i_<8;++i_)onesv[i_]=(short)0x3F80;
;   asm volatile("":"+v"(onesv));
;   const int qrel=wid*QBLK+r32;
;   const int qk0=q0+qrel-kt0*KVBLK-4*hi;
;     ...
;   bool resc=false;
;     ...
;   f32x16 pA0,pA1,pB0,pB1;
;   int sl_prev=0,sl_cur=0,sl_next=SLOTB,sl_n2=2*SLOTB;
;     ...
;   DMA_K(2,2*SLOTB);DMA_K(3,3*SLOTB);DMA_V(1,SLOTB);
;   WAIT_BAR(5);
;   qkt(pA0,pA1,Kbase,qr,(NOMAX?f32x16{}:negm),r32,hi);asm volatile("s_nop 15\n\ts_nop 7":"+v"(pA0),"+v"(pA1));CMASK(pA0,pA1,0);
;   START(pA0,pA1);
;   _Pragma("unroll") for(int r=0;r<16;++r)pA1[r]=__builtin_amdgcn_exp2f(pA1[r]);
;   WAIT_BAR(2);
;   DMA_K(4,4*SLOTB);DMA_V(2,2*SLOTB);
;   ROT();
;   kload8(kf,kp0+sl_cur);
.Lkvs_noprio:
	v_mul_u32_u24_e32 v214, 0xc00, v129
	s_lshl_b32 s10, s30, 4
	v_add_u32_e32 v214, s10, v214
	v_lshrrev_b32_e32 v215, 2, v129
	s_lshl_b32 s10, s5, 4
	v_add_u32_e32 v215, s10, v215
	v_mul_u32_u24_e32 v215, 0xc00, v215
	v_and_b32_e32 v217, 3, v129
	v_lshlrev_b32_e32 v217, 4, v217
	s_lshl_b32 s10, s57, 6
	v_add3_u32 v215, v215, v217, s10
	v_add_u32_e32 v203, 64, v214
	v_add_u32_e32 v204, 64, v215
	s_add_u32 s28, s28, 0x400
	s_addc_u32 s29, s29, 0
	s_add_u32 s36, s28, 0x100
	s_addc_u32 s37, s29, 0
	s_lshl_b32 s38, s30, 10
	s_add_i32 s39, s38, 0xa000
	v_lshrrev_b32_e32 v202, 5, v129
	v_lshlrev_b32_e32 v202, 10, v202
	v_lshl_add_u32 v202, v0, 4, v202
	s_lshl_b32 s10, s57, 9
	v_add_u32_e32 v202, s10, v202
	v_lshlrev_b32_e32 v217, 1, v129
	v_and_b32_e32 v217, 32, v217
	v_and_b32_e32 v126, 3, v129
	v_lshl_add_u32 v217, v126, 3, v217
	v_lshlrev_b32_e32 v126, 4, v129
	v_and_b32_e32 v126, 0xc0, v126
	v_lshrrev_b32_e32 v127, 5, v129
	v_lshl_or_b32 v126, v127, 8, v126
	s_lshl_b32 s10, s57, 11
	v_add3_u32 v217, v217, v126, s10
	s_mul_i32 s10, s4, 0xc00
	s_mul_hi_i32 s11, s4, 0xc00
	s_add_u32 s10, s52, s10
	s_addc_u32 s11, s53, s11
	s_add_u32 s14, s10, 0x18000
	s_addc_u32 s15, s11, 0
	v_mul_u32_u24_e32 v126, 0xc00, v0
	v_lshl_or_b32 v126, v127, 4, v126
	s_mov_b32 m0, s38
	s_nop 0
	global_load_lds_dwordx4 v214, s[28:29]
	s_mov_b32 m0, s39
	s_nop 0
	global_load_lds_dwordx4 v215, s[36:37]
	s_add_u32 s28, s28, 0x30000
	s_addc_u32 s29, s29, 0
	s_add_i32 m0, s38, 0x2000
	s_nop 0
	global_load_lds_dwordx4 v214, s[28:29]
	global_load_dwordx4 v[146:149], v126, s[10:11]
	global_load_dwordx4 v[150:153], v126, s[10:11] offset:32
	global_load_dwordx4 v[154:157], v126, s[10:11] offset:64
	global_load_dwordx4 v[158:161], v126, s[10:11] offset:96
	global_load_dwordx4 v[162:165], v126, s[14:15]
	global_load_dwordx4 v[166:169], v126, s[14:15] offset:32
	global_load_dwordx4 v[170:173], v126, s[14:15] offset:64
	global_load_dwordx4 v[174:177], v126, s[14:15] offset:96
	s_add_u32 s28, s28, 0x30000
	s_addc_u32 s29, s29, 0
	s_add_i32 m0, s38, 0x4000
	s_nop 0
	global_load_lds_dwordx4 v214, s[28:29]
	s_add_u32 s28, s28, 0x30000
	s_addc_u32 s29, s29, 0
	s_add_i32 m0, s38, 0x6000
	s_nop 0
	global_load_lds_dwordx4 v214, s[28:29]
	s_add_u32 s36, s36, 0x30000
	s_addc_u32 s37, s37, 0
	s_add_i32 m0, s39, 0x2000
	s_nop 0
	global_load_lds_dwordx4 v215, s[36:37]
	s_add_u32 s28, s28, 0x30000
	s_addc_u32 s29, s29, 0
	s_add_u32 s36, s36, 0x30000
	s_addc_u32 s37, s37, 0
	v_mov_b32_e32 v126, 0
	v_mov_b32_e32 v127, 0
	v_mov_b32_e32 v2, 0
	v_mov_b32_e32 v3, 0
	v_mov_b32_e32 v4, 0
	v_mov_b32_e32 v5, 0
	v_mov_b32_e32 v6, 0
	v_mov_b32_e32 v7, 0
	v_mov_b32_e32 v8, 0
	v_mov_b32_e32 v9, 0
	v_mov_b32_e32 v10, 0
	v_mov_b32_e32 v11, 0
	v_mov_b32_e32 v12, 0
	v_mov_b32_e32 v13, 0
	v_mov_b32_e32 v14, 0
	v_mov_b32_e32 v15, 0
	v_mov_b32_e32 v16, 0
	v_mov_b32_e32 v17, 0
	v_mov_b32_e32 v18, 0
	v_mov_b32_e32 v19, 0
	v_mov_b32_e32 v20, 0
	v_mov_b32_e32 v21, 0
	v_mov_b32_e32 v22, 0
	v_mov_b32_e32 v23, 0
	v_mov_b32_e32 v24, 0
	v_mov_b32_e32 v25, 0
	v_mov_b32_e32 v26, 0
	v_mov_b32_e32 v27, 0
	v_mov_b32_e32 v28, 0
	v_mov_b32_e32 v29, 0
	v_mov_b32_e32 v30, 0
	v_mov_b32_e32 v31, 0
	v_mov_b32_e32 v32, 0
	v_mov_b32_e32 v33, 0
	v_mov_b32_e32 v34, 0
	v_mov_b32_e32 v35, 0
	v_mov_b32_e32 v36, 0
	v_mov_b32_e32 v37, 0
	v_mov_b32_e32 v38, 0
	v_mov_b32_e32 v39, 0
	v_mov_b32_e32 v40, 0
	v_mov_b32_e32 v41, 0
	v_mov_b32_e32 v42, 0
	v_mov_b32_e32 v43, 0
	v_mov_b32_e32 v44, 0
	v_mov_b32_e32 v45, 0
	v_mov_b32_e32 v46, 0
	v_mov_b32_e32 v47, 0
	v_mov_b32_e32 v48, 0
	v_mov_b32_e32 v49, 0
	v_mov_b32_e32 v50, 0
	v_mov_b32_e32 v51, 0
	v_mov_b32_e32 v52, 0
	v_mov_b32_e32 v53, 0
	v_mov_b32_e32 v54, 0
	v_mov_b32_e32 v55, 0
	v_mov_b32_e32 v56, 0
	v_mov_b32_e32 v57, 0
	v_mov_b32_e32 v58, 0
	v_mov_b32_e32 v59, 0
	v_mov_b32_e32 v60, 0
	v_mov_b32_e32 v61, 0
	v_mov_b32_e32 v62, 0
	v_mov_b32_e32 v63, 0
	v_mov_b32_e32 v64, 0
	v_mov_b32_e32 v65, 0
	s_waitcnt vmcnt(3)
	s_barrier
	ds_read_b128 v[178:181], v202
	ds_read_b128 v[182:185], v202 offset:2048
	ds_read_b128 v[186:189], v202 offset:4096
	ds_read_b128 v[114:117], v202 offset:6144
	s_waitcnt lgkmcnt(0)
	v_mfma_f32_32x32x16_bf16 v[66:81], v[178:181], v[146:149], 0
	v_mfma_f32_32x32x16_bf16 v[82:97], v[178:181], v[162:165], 0
	v_mfma_f32_32x32x16_bf16 v[66:81], v[182:185], v[150:153], v[66:81]
	v_mfma_f32_32x32x16_bf16 v[82:97], v[182:185], v[166:169], v[82:97]
	v_mfma_f32_32x32x16_bf16 v[66:81], v[186:189], v[154:157], v[66:81]
	v_mfma_f32_32x32x16_bf16 v[82:97], v[186:189], v[170:173], v[82:97]
	v_mfma_f32_32x32x16_bf16 v[66:81], v[114:117], v[158:161], v[66:81]
	v_mfma_f32_32x32x16_bf16 v[82:97], v[114:117], v[174:177], v[82:97]
	s_nop 15
	s_nop 7
	v_exp_f32_e32 v66, v66
	v_exp_f32_e32 v67, v67
	v_exp_f32_e32 v68, v68
	v_exp_f32_e32 v69, v69
	v_exp_f32_e32 v70, v70
	v_exp_f32_e32 v71, v71
	v_exp_f32_e32 v72, v72
	v_exp_f32_e32 v73, v73
	v_exp_f32_e32 v74, v74
	v_exp_f32_e32 v75, v75
	v_exp_f32_e32 v76, v76
	v_exp_f32_e32 v77, v77
	v_exp_f32_e32 v78, v78
	v_exp_f32_e32 v79, v79
	v_exp_f32_e32 v80, v80
	v_exp_f32_e32 v81, v81
	v_exp_f32_e32 v82, v82
	v_exp_f32_e32 v83, v83
	v_exp_f32_e32 v84, v84
	v_exp_f32_e32 v85, v85
	v_exp_f32_e32 v86, v86
	v_exp_f32_e32 v87, v87
	v_exp_f32_e32 v88, v88
	v_exp_f32_e32 v89, v89
	v_exp_f32_e32 v90, v90
	v_exp_f32_e32 v91, v91
	v_exp_f32_e32 v92, v92
	v_exp_f32_e32 v93, v93
	v_exp_f32_e32 v94, v94
	v_exp_f32_e32 v95, v95
	v_exp_f32_e32 v96, v96
	v_exp_f32_e32 v97, v97
	s_waitcnt vmcnt(0) lgkmcnt(0)
	s_barrier
	s_add_i32 m0, s38, 0x8000
	s_nop 0
	global_load_lds_dwordx4 v214, s[28:29]
	s_add_i32 m0, s39, 0x4000
	s_nop 0
	global_load_lds_dwordx4 v215, s[36:37]
	s_add_u32 s28, s28, 0x30000
	s_addc_u32 s29, s29, 0
	s_add_u32 s36, s36, 0x30000
	s_addc_u32 s37, s37, 0
	s_mov_b32 s15, 0
	s_movk_i32 s14, 0x2000
	s_movk_i32 s44, 0x4000
	s_movk_i32 s51, 0x6000
	v_add_u32_e32 v129, s14, v202
	ds_read_b128 v[178:181], v129
	ds_read_b128 v[182:185], v129 offset:2048
	ds_read_b128 v[186:189], v129 offset:4096
	ds_read_b128 v[114:117], v129 offset:6144
	s_mov_b32 s18, 1
	s_waitcnt lgkmcnt(3)
	v_mfma_f32_32x32x16_bf16 v[98:113], v[178:181], v[146:149], 0
	s_cmp_eq_u32 s57, 0
	s_cbranch_scc1 .Lkvs_loopA
; #define WAIT_BAR(N) asm volatile("s_waitcnt vmcnt(" #N ") lgkmcnt(0)\n\ts_barrier":::"memory")
;   #define RESC() do{ if(resc){ asm volatile("s_waitcnt lgkmcnt(0)":::"memory"); \
;       _Pragma("unroll") for(int d_=0;d_<2;++d_) _Pragma("unroll") for(int r=0;r<16;++r)o[d_][r]*=wsf[crow(r,hi)]; } }while(0)
;   #define ROT() do{sl_prev=sl_cur;sl_cur=sl_next;sl_next=sl_n2;sl_n2=(sl_n2==(NSLOT-1)*SLOTB)?0:sl_n2+SLOTB;}while(0)
; template<int MODE,int THRL,bool NOMAX> __device__ __forceinline__ void attn_unit(const bf16*Qs,const bf16*__restrict__ Ks,const bf16*__restrict__ Vs,bf16*Os,int S,int q0,float sink2,float slope2,float*ssq,char*shm,int tid_in){
;     ...
;   for(;t+5<NT;t+=2){
;     STEP(pB0,pB1,pA0,pA1,t,true,true,true);     WAIT_BAR(2); RESC(); ROT();
;     STEP(pA0,pA1,pB0,pB1,t+1,true,true,true);   RESC(); ROT();
;   }
.Lkvs_loopB:
	v_add_u32_e32 v129, s15, v217
	ds_read_b64_tr_b16 v[210:211], v129 offset:40960
	v_add_f32_e32 v0, v66, v67
	v_add_f32_e32 v0, v68, v0
	v_add_f32_e32 v0, v69, v0
	v_cvt_pk_bf16_f32 v190, v66, v67
	v_cvt_pk_bf16_f32 v191, v68, v69
	v_mfma_f32_32x32x16_bf16 v[130:145], v[178:181], v[162:165], 0
	ds_read_b64_tr_b16 v[212:213], v129 offset:41472
	v_add_f32_e32 v0, v70, v0
	v_add_f32_e32 v0, v71, v0
	v_add_f32_e32 v0, v72, v0
	v_add_f32_e32 v0, v73, v0
	v_cvt_pk_bf16_f32 v192, v70, v71
	v_cvt_pk_bf16_f32 v193, v72, v73
	s_waitcnt lgkmcnt(4)
	v_mfma_f32_32x32x16_bf16 v[98:113], v[182:185], v[150:153], v[98:113]
	ds_read_b64_tr_b16 v[118:119], v129 offset:45056
	v_add_f32_e32 v0, v74, v0
	v_add_f32_e32 v0, v75, v0
	v_add_f32_e32 v0, v76, v0
	v_add_f32_e32 v0, v77, v0
	v_cvt_pk_bf16_f32 v194, v74, v75
	v_cvt_pk_bf16_f32 v195, v76, v77
	v_mfma_f32_32x32x16_bf16 v[130:145], v[182:185], v[166:169], v[130:145]
	ds_read_b64_tr_b16 v[120:121], v129 offset:45568
	v_add_f32_e32 v0, v78, v0
	v_add_f32_e32 v0, v79, v0
	v_add_f32_e32 v0, v80, v0
	v_add_f32_e32 v0, v81, v0
	v_add_f32_e32 v126, v126, v0
	v_cvt_pk_bf16_f32 v196, v78, v79
	v_cvt_pk_bf16_f32 v197, v80, v81
	s_waitcnt lgkmcnt(5)
	v_mfma_f32_32x32x16_bf16 v[98:113], v[186:189], v[154:157], v[98:113]
	ds_read_b64_tr_b16 v[122:123], v129 offset:41984
	v_add_f32_e32 v0, v82, v83
	v_add_f32_e32 v0, v84, v0
	v_add_f32_e32 v0, v85, v0
	v_cvt_pk_bf16_f32 v198, v82, v83
	v_cvt_pk_bf16_f32 v199, v84, v85
	v_mfma_f32_32x32x16_bf16 v[130:145], v[186:189], v[170:173], v[130:145]
	ds_read_b64_tr_b16 v[124:125], v129 offset:42496
	v_add_f32_e32 v0, v86, v0
	v_add_f32_e32 v0, v87, v0
	v_add_f32_e32 v0, v88, v0
	v_add_f32_e32 v0, v89, v0
	v_cvt_pk_bf16_f32 v200, v86, v87
	v_cvt_pk_bf16_f32 v201, v88, v89
	s_waitcnt lgkmcnt(6)
	v_mfma_f32_32x32x16_bf16 v[98:113], v[114:117], v[158:161], v[98:113]
	ds_read_b64_tr_b16 v[218:219], v129 offset:46080
	v_add_f32_e32 v0, v90, v0
	v_add_f32_e32 v0, v91, v0
	v_add_f32_e32 v0, v92, v0
	v_add_f32_e32 v0, v93, v0
	v_cvt_pk_bf16_f32 v206, v90, v91
	v_cvt_pk_bf16_f32 v207, v92, v93
	v_mfma_f32_32x32x16_bf16 v[130:145], v[114:117], v[174:177], v[130:145]
	ds_read_b64_tr_b16 v[220:221], v129 offset:46592
	v_add_f32_e32 v0, v94, v0
	v_add_f32_e32 v0, v95, v0
	v_add_f32_e32 v0, v96, v0
	v_add_f32_e32 v0, v97, v0
	v_add_f32_e32 v127, v127, v0
	v_cvt_pk_bf16_f32 v208, v94, v95
	v_cvt_pk_bf16_f32 v209, v96, v97
	s_waitcnt lgkmcnt(6)
	v_mfma_f32_32x32x16_bf16 v[2:17], v[190:193], v[210:213], v[2:17]
	v_add_u32_e32 v129, s44, v202
	v_exp_f32_e32 v98, v98
	v_exp_f32_e32 v99, v99
	v_exp_f32_e32 v100, v100
	v_exp_f32_e32 v101, v101
	s_waitcnt lgkmcnt(4)
	v_mfma_f32_32x32x16_bf16 v[18:33], v[190:193], v[118:121], v[18:33]
	ds_read_b128 v[178:181], v129
	v_exp_f32_e32 v102, v102
	v_exp_f32_e32 v103, v103
	v_exp_f32_e32 v104, v104
	v_exp_f32_e32 v105, v105
	v_mfma_f32_32x32x16_bf16 v[34:49], v[198:201], v[210:213], v[34:49]
	ds_read_b128 v[182:185], v129 offset:2048
	v_exp_f32_e32 v106, v106
	v_exp_f32_e32 v107, v107
	v_exp_f32_e32 v108, v108
	v_exp_f32_e32 v109, v109
	v_mfma_f32_32x32x16_bf16 v[50:65], v[198:201], v[118:121], v[50:65]
	ds_read_b128 v[186:189], v129 offset:4096
	v_exp_f32_e32 v110, v110
	v_exp_f32_e32 v111, v111
	v_exp_f32_e32 v112, v112
	v_exp_f32_e32 v113, v113
	s_waitcnt lgkmcnt(5)
	v_mfma_f32_32x32x16_bf16 v[2:17], v[194:197], v[122:125], v[2:17]
	ds_read_b128 v[114:117], v129 offset:6144
	v_exp_f32_e32 v130, v130
	v_exp_f32_e32 v131, v131
	v_exp_f32_e32 v132, v132
	v_exp_f32_e32 v133, v133
	s_waitcnt lgkmcnt(4)
	v_mfma_f32_32x32x16_bf16 v[18:33], v[194:197], v[218:221], v[18:33]
	v_exp_f32_e32 v134, v134
	v_exp_f32_e32 v135, v135
	v_exp_f32_e32 v136, v136
	v_exp_f32_e32 v137, v137
	v_mfma_f32_32x32x16_bf16 v[34:49], v[206:209], v[122:125], v[34:49]
	v_exp_f32_e32 v138, v138
	v_exp_f32_e32 v139, v139
	v_exp_f32_e32 v140, v140
	v_exp_f32_e32 v141, v141
	v_mfma_f32_32x32x16_bf16 v[50:65], v[206:209], v[218:221], v[50:65]
	v_exp_f32_e32 v142, v142
	v_exp_f32_e32 v143, v143
	v_exp_f32_e32 v144, v144
	v_exp_f32_e32 v145, v145
	s_waitcnt lgkmcnt(3)
	v_mfma_f32_32x32x16_bf16 v[66:81], v[178:181], v[146:149], 0
	s_mov_b32 s15, s14
	s_mov_b32 s14, s44
	s_mov_b32 s44, s51
	s_add_i32 s10, s51, 0x2000
	s_cmpk_lg_u32 s51, 0x8000
	s_cselect_b32 s51, s10, 0
	s_waitcnt vmcnt(0) lgkmcnt(0)
	s_barrier
; #define WAIT_BAR(N) asm volatile("s_waitcnt vmcnt(" #N ") lgkmcnt(0)\n\ts_barrier":::"memory")
;   #define RESC() do{ if(resc){ asm volatile("s_waitcnt lgkmcnt(0)":::"memory"); \
;       _Pragma("unroll") for(int d_=0;d_<2;++d_) _Pragma("unroll") for(int r=0;r<16;++r)o[d_][r]*=wsf[crow(r,hi)]; } }while(0)
;   #define ROT() do{sl_prev=sl_cur;sl_cur=sl_next;sl_next=sl_n2;sl_n2=(sl_n2==(NSLOT-1)*SLOTB)?0:sl_n2+SLOTB;}while(0)
; template<int MODE,int THRL,bool NOMAX> __device__ __forceinline__ void attn_unit(const bf16*Qs,const bf16*__restrict__ Ks,const bf16*__restrict__ Vs,bf16*Os,int S,int q0,float sink2,float slope2,float*ssq,char*shm,int tid_in){
;     ...
;   for(;t+5<NT;t+=2){
;     STEP(pB0,pB1,pA0,pA1,t,true,true,true);     WAIT_BAR(2); RESC(); ROT();
;     STEP(pA0,pA1,pB0,pB1,t+1,true,true,true);   RESC(); ROT();
;   }
	v_add_u32_e32 v129, s15, v217
	ds_read_b64_tr_b16 v[210:211], v129 offset:40960
	v_add_f32_e32 v0, v98, v99
	v_add_f32_e32 v0, v100, v0
	v_add_f32_e32 v0, v101, v0
	v_cvt_pk_bf16_f32 v190, v98, v99
	v_cvt_pk_bf16_f32 v191, v100, v101
	v_mfma_f32_32x32x16_bf16 v[82:97], v[178:181], v[162:165], 0
	ds_read_b64_tr_b16 v[212:213], v129 offset:41472
	v_add_f32_e32 v0, v102, v0
	v_add_f32_e32 v0, v103, v0
	v_add_f32_e32 v0, v104, v0
	v_add_f32_e32 v0, v105, v0
	v_cvt_pk_bf16_f32 v192, v102, v103
	v_cvt_pk_bf16_f32 v193, v104, v105
	s_waitcnt lgkmcnt(4)
	v_mfma_f32_32x32x16_bf16 v[66:81], v[182:185], v[150:153], v[66:81]
	ds_read_b64_tr_b16 v[118:119], v129 offset:45056
	v_add_f32_e32 v0, v106, v0
	v_add_f32_e32 v0, v107, v0
	v_add_f32_e32 v0, v108, v0
	v_add_f32_e32 v0, v109, v0
	v_cvt_pk_bf16_f32 v194, v106, v107
	v_cvt_pk_bf16_f32 v195, v108, v109
	v_mfma_f32_32x32x16_bf16 v[82:97], v[182:185], v[166:169], v[82:97]
	ds_read_b64_tr_b16 v[120:121], v129 offset:45568
	v_add_f32_e32 v0, v110, v0
	v_add_f32_e32 v0, v111, v0
	v_add_f32_e32 v0, v112, v0
	v_add_f32_e32 v0, v113, v0
	v_add_f32_e32 v126, v126, v0
	v_cvt_pk_bf16_f32 v196, v110, v111
	v_cvt_pk_bf16_f32 v197, v112, v113
	s_waitcnt lgkmcnt(5)
	v_mfma_f32_32x32x16_bf16 v[66:81], v[186:189], v[154:157], v[66:81]
	ds_read_b64_tr_b16 v[122:123], v129 offset:41984
	v_add_f32_e32 v0, v130, v131
	v_add_f32_e32 v0, v132, v0
	v_add_f32_e32 v0, v133, v0
	v_cvt_pk_bf16_f32 v198, v130, v131
	v_cvt_pk_bf16_f32 v199, v132, v133
	v_mfma_f32_32x32x16_bf16 v[82:97], v[186:189], v[170:173], v[82:97]
	ds_read_b64_tr_b16 v[124:125], v129 offset:42496
	v_add_f32_e32 v0, v134, v0
	v_add_f32_e32 v0, v135, v0
	v_add_f32_e32 v0, v136, v0
	v_add_f32_e32 v0, v137, v0
	v_cvt_pk_bf16_f32 v200, v134, v135
	v_cvt_pk_bf16_f32 v201, v136, v137
	s_waitcnt lgkmcnt(6)
	v_mfma_f32_32x32x16_bf16 v[66:81], v[114:117], v[158:161], v[66:81]
	ds_read_b64_tr_b16 v[218:219], v129 offset:46080
	v_add_f32_e32 v0, v138, v0
	v_add_f32_e32 v0, v139, v0
	v_add_f32_e32 v0, v140, v0
	v_add_f32_e32 v0, v141, v0
	v_cvt_pk_bf16_f32 v206, v138, v139
	v_cvt_pk_bf16_f32 v207, v140, v141
	v_mfma_f32_32x32x16_bf16 v[82:97], v[114:117], v[174:177], v[82:97]
	ds_read_b64_tr_b16 v[220:221], v129 offset:46592
	v_add_f32_e32 v0, v142, v0
	v_add_f32_e32 v0, v143, v0
	v_add_f32_e32 v0, v144, v0
	v_add_f32_e32 v0, v145, v0
	v_add_f32_e32 v127, v127, v0
	v_cvt_pk_bf16_f32 v208, v142, v143
	v_cvt_pk_bf16_f32 v209, v144, v145
	s_waitcnt lgkmcnt(6)
	v_mfma_f32_32x32x16_bf16 v[2:17], v[190:193], v[210:213], v[2:17]
	v_add_u32_e32 v129, s44, v202
	v_exp_f32_e32 v66, v66
	v_exp_f32_e32 v67, v67
	v_exp_f32_e32 v68, v68
	v_exp_f32_e32 v69, v69
	s_waitcnt lgkmcnt(4)
	v_mfma_f32_32x32x16_bf16 v[18:33], v[190:193], v[118:121], v[18:33]
	ds_read_b128 v[178:181], v129
	v_exp_f32_e32 v70, v70
	v_exp_f32_e32 v71, v71
	v_exp_f32_e32 v72, v72
	v_exp_f32_e32 v73, v73
	v_mfma_f32_32x32x16_bf16 v[34:49], v[198:201], v[210:213], v[34:49]
	ds_read_b128 v[182:185], v129 offset:2048
	v_exp_f32_e32 v74, v74
	v_exp_f32_e32 v75, v75
	v_exp_f32_e32 v76, v76
	v_exp_f32_e32 v77, v77
	v_mfma_f32_32x32x16_bf16 v[50:65], v[198:201], v[118:121], v[50:65]
	ds_read_b128 v[186:189], v129 offset:4096
	v_exp_f32_e32 v78, v78
	v_exp_f32_e32 v79, v79
	v_exp_f32_e32 v80, v80
	v_exp_f32_e32 v81, v81
	s_waitcnt lgkmcnt(5)
	v_mfma_f32_32x32x16_bf16 v[2:17], v[194:197], v[122:125], v[2:17]
	ds_read_b128 v[114:117], v129 offset:6144
	v_exp_f32_e32 v82, v82
	v_exp_f32_e32 v83, v83
	v_exp_f32_e32 v84, v84
	v_exp_f32_e32 v85, v85
	s_waitcnt lgkmcnt(4)
	v_mfma_f32_32x32x16_bf16 v[18:33], v[194:197], v[218:221], v[18:33]
	v_exp_f32_e32 v86, v86
	v_exp_f32_e32 v87, v87
	v_exp_f32_e32 v88, v88
	v_exp_f32_e32 v89, v89
	v_mfma_f32_32x32x16_bf16 v[34:49], v[206:209], v[122:125], v[34:49]
	v_exp_f32_e32 v90, v90
	v_exp_f32_e32 v91, v91
	v_exp_f32_e32 v92, v92
	v_exp_f32_e32 v93, v93
	v_mfma_f32_32x32x16_bf16 v[50:65], v[206:209], v[218:221], v[50:65]
	v_exp_f32_e32 v94, v94
	v_exp_f32_e32 v95, v95
	v_exp_f32_e32 v96, v96
	v_exp_f32_e32 v97, v97
	s_waitcnt lgkmcnt(3)
	v_mfma_f32_32x32x16_bf16 v[98:113], v[178:181], v[146:149], 0
	s_mov_b32 s15, s14
	s_mov_b32 s14, s44
	s_mov_b32 s44, s51
	s_add_i32 s10, s51, 0x2000
	s_cmpk_lg_u32 s51, 0x8000
	s_cselect_b32 s51, s10, 0
	s_add_i32 s18, s18, 2
	s_add_i32 s10, s18, 1
	s_cmp_lt_u32 s10, s40
	s_cbranch_scc1 .Lkvs_loopB
; #define WAIT_BAR(N) asm volatile("s_waitcnt vmcnt(" #N ") lgkmcnt(0)\n\ts_barrier":::"memory")
;   #define RESC() do{ if(resc){ asm volatile("s_waitcnt lgkmcnt(0)":::"memory"); \
;       _Pragma("unroll") for(int d_=0;d_<2;++d_) _Pragma("unroll") for(int r=0;r<16;++r)o[d_][r]*=wsf[crow(r,hi)]; } }while(0)
;   #define ROT() do{sl_prev=sl_cur;sl_cur=sl_next;sl_next=sl_n2;sl_n2=(sl_n2==(NSLOT-1)*SLOTB)?0:sl_n2+SLOTB;}while(0)
;   #define ENDW(tt) do{ if((tt)+4<NT){WAIT_BAR(2);} else if((tt)+2<NT){WAIT_BAR(1);} else {WAIT_BAR(0);} }while(0)
; template<int MODE,int THRL,bool NOMAX> __device__ __forceinline__ void attn_unit(const bf16*Qs,const bf16*__restrict__ Ks,const bf16*__restrict__ Vs,bf16*Os,int S,int q0,float sink2,float slope2,float*ssq,char*shm,int tid_in){
;     ...
;   for(;t+1<NT;t+=2){
;     STEP(pB0,pB1,pA0,pA1,t,(t+4<NT),(t+2<NT),(t+1<NT));       ENDW(t);   RESC(); ROT();
;     STEP(pA0,pA1,pB0,pB1,t+1,(t+5<NT),(t+3<NT),(t+2<NT));     if(t+3>=NT){WAIT_BAR(0);} RESC(); ROT();
;   }
;   STEP(pB0,pB1,pA0,pA1,NT-1,false,false,false); RESC();
	v_add_u32_e32 v129, s15, v217
	ds_read_b64_tr_b16 v[210:211], v129 offset:40960
	v_add_f32_e32 v0, v66, v67
	v_add_f32_e32 v0, v68, v0
	v_add_f32_e32 v0, v69, v0
	v_cvt_pk_bf16_f32 v190, v66, v67
	v_cvt_pk_bf16_f32 v191, v68, v69
	v_mfma_f32_32x32x16_bf16 v[130:145], v[178:181], v[162:165], 0
	ds_read_b64_tr_b16 v[212:213], v129 offset:41472
	v_add_f32_e32 v0, v70, v0
	v_add_f32_e32 v0, v71, v0
	v_add_f32_e32 v0, v72, v0
	v_add_f32_e32 v0, v73, v0
	v_cvt_pk_bf16_f32 v192, v70, v71
	v_cvt_pk_bf16_f32 v193, v72, v73
	s_waitcnt lgkmcnt(4)
	v_mfma_f32_32x32x16_bf16 v[98:113], v[182:185], v[150:153], v[98:113]
	ds_read_b64_tr_b16 v[118:119], v129 offset:45056
	v_add_f32_e32 v0, v74, v0
	v_add_f32_e32 v0, v75, v0
	v_add_f32_e32 v0, v76, v0
	v_add_f32_e32 v0, v77, v0
	v_cvt_pk_bf16_f32 v194, v74, v75
	v_cvt_pk_bf16_f32 v195, v76, v77
	v_mfma_f32_32x32x16_bf16 v[130:145], v[182:185], v[166:169], v[130:145]
	ds_read_b64_tr_b16 v[120:121], v129 offset:45568
	v_add_f32_e32 v0, v78, v0
	v_add_f32_e32 v0, v79, v0
	v_add_f32_e32 v0, v80, v0
	v_add_f32_e32 v0, v81, v0
	v_add_f32_e32 v126, v126, v0
	v_cvt_pk_bf16_f32 v196, v78, v79
	v_cvt_pk_bf16_f32 v197, v80, v81
	s_waitcnt lgkmcnt(5)
	v_mfma_f32_32x32x16_bf16 v[98:113], v[186:189], v[154:157], v[98:113]
	ds_read_b64_tr_b16 v[122:123], v129 offset:41984
	v_add_f32_e32 v0, v82, v83
	v_add_f32_e32 v0, v84, v0
	v_add_f32_e32 v0, v85, v0
	v_cvt_pk_bf16_f32 v198, v82, v83
	v_cvt_pk_bf16_f32 v199, v84, v85
	v_mfma_f32_32x32x16_bf16 v[130:145], v[186:189], v[170:173], v[130:145]
	ds_read_b64_tr_b16 v[124:125], v129 offset:42496
	v_add_f32_e32 v0, v86, v0
	v_add_f32_e32 v0, v87, v0
	v_add_f32_e32 v0, v88, v0
	v_add_f32_e32 v0, v89, v0
	v_cvt_pk_bf16_f32 v200, v86, v87
	v_cvt_pk_bf16_f32 v201, v88, v89
	s_waitcnt lgkmcnt(6)
	v_mfma_f32_32x32x16_bf16 v[98:113], v[114:117], v[158:161], v[98:113]
	ds_read_b64_tr_b16 v[218:219], v129 offset:46080
	v_add_f32_e32 v0, v90, v0
	v_add_f32_e32 v0, v91, v0
	v_add_f32_e32 v0, v92, v0
	v_add_f32_e32 v0, v93, v0
	v_cvt_pk_bf16_f32 v206, v90, v91
	v_cvt_pk_bf16_f32 v207, v92, v93
	v_mfma_f32_32x32x16_bf16 v[130:145], v[114:117], v[174:177], v[130:145]
	ds_read_b64_tr_b16 v[220:221], v129 offset:46592
	v_add_f32_e32 v0, v94, v0
	v_add_f32_e32 v0, v95, v0
	v_add_f32_e32 v0, v96, v0
	v_add_f32_e32 v0, v97, v0
	v_add_f32_e32 v127, v127, v0
	v_cvt_pk_bf16_f32 v208, v94, v95
	v_cvt_pk_bf16_f32 v209, v96, v97
	s_waitcnt lgkmcnt(6)
	v_mfma_f32_32x32x16_bf16 v[2:17], v[190:193], v[210:213], v[2:17]
	v_add_u32_e32 v129, s44, v202
	v_exp_f32_e32 v98, v98
	v_exp_f32_e32 v99, v99
	v_exp_f32_e32 v100, v100
	v_exp_f32_e32 v101, v101
	s_waitcnt lgkmcnt(4)
	v_mfma_f32_32x32x16_bf16 v[18:33], v[190:193], v[118:121], v[18:33]
	ds_read_b128 v[178:181], v129
	v_exp_f32_e32 v102, v102
	v_exp_f32_e32 v103, v103
	v_exp_f32_e32 v104, v104
	v_exp_f32_e32 v105, v105
	v_mfma_f32_32x32x16_bf16 v[34:49], v[198:201], v[210:213], v[34:49]
	ds_read_b128 v[182:185], v129 offset:2048
	v_exp_f32_e32 v106, v106
	v_exp_f32_e32 v107, v107
	v_exp_f32_e32 v108, v108
	v_exp_f32_e32 v109, v109
	v_mfma_f32_32x32x16_bf16 v[50:65], v[198:201], v[118:121], v[50:65]
	ds_read_b128 v[186:189], v129 offset:4096
	v_exp_f32_e32 v110, v110
	v_exp_f32_e32 v111, v111
	v_exp_f32_e32 v112, v112
	v_exp_f32_e32 v113, v113
	s_waitcnt lgkmcnt(5)
	v_mfma_f32_32x32x16_bf16 v[2:17], v[194:197], v[122:125], v[2:17]
	ds_read_b128 v[114:117], v129 offset:6144
	v_exp_f32_e32 v130, v130
	v_exp_f32_e32 v131, v131
	v_exp_f32_e32 v132, v132
	v_exp_f32_e32 v133, v133
	s_waitcnt lgkmcnt(4)
	v_mfma_f32_32x32x16_bf16 v[18:33], v[194:197], v[218:221], v[18:33]
	v_exp_f32_e32 v134, v134
	v_exp_f32_e32 v135, v135
	v_exp_f32_e32 v136, v136
	v_exp_f32_e32 v137, v137
	v_mfma_f32_32x32x16_bf16 v[34:49], v[206:209], v[122:125], v[34:49]
	v_exp_f32_e32 v138, v138
	v_exp_f32_e32 v139, v139
	v_exp_f32_e32 v140, v140
	v_exp_f32_e32 v141, v141
	v_mfma_f32_32x32x16_bf16 v[50:65], v[206:209], v[218:221], v[50:65]
	v_exp_f32_e32 v142, v142
	v_exp_f32_e32 v143, v143
	v_exp_f32_e32 v144, v144
	v_exp_f32_e32 v145, v145
	s_mov_b32 s15, s14
	s_mov_b32 s14, s44
	s_mov_b32 s44, s51
	s_add_i32 s10, s51, 0x2000
	s_cmpk_lg_u32 s51, 0x8000
	s_cselect_b32 s51, s10, 0
	s_waitcnt vmcnt(0) lgkmcnt(0)
	s_barrier
	s_branch .Lkvs_drain
; #define WAIT_BAR(N) asm volatile("s_waitcnt vmcnt(" #N ") lgkmcnt(0)\n\ts_barrier":::"memory")
;   #define RESC() do{ if(resc){ asm volatile("s_waitcnt lgkmcnt(0)":::"memory"); \
;       _Pragma("unroll") for(int d_=0;d_<2;++d_) _Pragma("unroll") for(int r=0;r<16;++r)o[d_][r]*=wsf[crow(r,hi)]; } }while(0)
;   #define ROT() do{sl_prev=sl_cur;sl_cur=sl_next;sl_next=sl_n2;sl_n2=(sl_n2==(NSLOT-1)*SLOTB)?0:sl_n2+SLOTB;}while(0)
; template<int MODE,int THRL,bool NOMAX> __device__ __forceinline__ void attn_unit(const bf16*Qs,const bf16*__restrict__ Ks,const bf16*__restrict__ Vs,bf16*Os,int S,int q0,float sink2,float slope2,float*ssq,char*shm,int tid_in){
;     ...
;   for(;t+5<NT;t+=2){
;     STEP(pB0,pB1,pA0,pA1,t,true,true,true);     WAIT_BAR(2); RESC(); ROT();
;     STEP(pA0,pA1,pB0,pB1,t+1,true,true,true);   RESC(); ROT();
;   }
.Lkvs_loopA:
	v_add_u32_e32 v129, s15, v217
	ds_read_b64_tr_b16 v[210:211], v129 offset:40960
	v_add_f32_e32 v0, v66, v67
	v_add_f32_e32 v0, v68, v0
	v_add_f32_e32 v0, v69, v0
	v_cvt_pk_bf16_f32 v190, v66, v67
	v_cvt_pk_bf16_f32 v191, v68, v69
	v_mfma_f32_32x32x16_bf16 v[130:145], v[178:181], v[162:165], 0
	ds_read_b64_tr_b16 v[212:213], v129 offset:41472
	v_add_f32_e32 v0, v70, v0
	v_add_f32_e32 v0, v71, v0
	v_add_f32_e32 v0, v72, v0
	v_add_f32_e32 v0, v73, v0
	v_cvt_pk_bf16_f32 v192, v70, v71
	v_cvt_pk_bf16_f32 v193, v72, v73
	s_add_i32 s10, s15, s38
	s_mov_b32 m0, s10
	s_nop 0
	global_load_lds_dwordx4 v214, s[28:29]
	s_add_i32 s10, s10, 0x1000
	s_mov_b32 m0, s10
	s_nop 0
	global_load_lds_dwordx4 v203, s[28:29]
	s_add_u32 s28, s28, 0x30000
	s_addc_u32 s29, s29, 0
	s_waitcnt lgkmcnt(4)
	v_mfma_f32_32x32x16_bf16 v[98:113], v[182:185], v[150:153], v[98:113]
	ds_read_b64_tr_b16 v[118:119], v129 offset:45056
	v_add_f32_e32 v0, v74, v0
	v_add_f32_e32 v0, v75, v0
	v_add_f32_e32 v0, v76, v0
	v_add_f32_e32 v0, v77, v0
	v_cvt_pk_bf16_f32 v194, v74, v75
	v_cvt_pk_bf16_f32 v195, v76, v77
	v_mfma_f32_32x32x16_bf16 v[130:145], v[182:185], v[166:169], v[130:145]
	ds_read_b64_tr_b16 v[120:121], v129 offset:45568
	v_add_f32_e32 v0, v78, v0
	v_add_f32_e32 v0, v79, v0
	v_add_f32_e32 v0, v80, v0
	v_add_f32_e32 v0, v81, v0
	v_add_f32_e32 v126, v126, v0
	v_cvt_pk_bf16_f32 v196, v78, v79
	v_cvt_pk_bf16_f32 v197, v80, v81
	s_waitcnt lgkmcnt(5)
	v_mfma_f32_32x32x16_bf16 v[98:113], v[186:189], v[154:157], v[98:113]
	ds_read_b64_tr_b16 v[122:123], v129 offset:41984
	v_add_f32_e32 v0, v82, v83
	v_add_f32_e32 v0, v84, v0
	v_add_f32_e32 v0, v85, v0
	v_cvt_pk_bf16_f32 v198, v82, v83
	v_cvt_pk_bf16_f32 v199, v84, v85
	v_mfma_f32_32x32x16_bf16 v[130:145], v[186:189], v[170:173], v[130:145]
	ds_read_b64_tr_b16 v[124:125], v129 offset:42496
	v_add_f32_e32 v0, v86, v0
	v_add_f32_e32 v0, v87, v0
	v_add_f32_e32 v0, v88, v0
	v_add_f32_e32 v0, v89, v0
	v_cvt_pk_bf16_f32 v200, v86, v87
	v_cvt_pk_bf16_f32 v201, v88, v89
	s_waitcnt lgkmcnt(6)
	v_mfma_f32_32x32x16_bf16 v[98:113], v[114:117], v[158:161], v[98:113]
	ds_read_b64_tr_b16 v[218:219], v129 offset:46080
	v_add_f32_e32 v0, v90, v0
	v_add_f32_e32 v0, v91, v0
	v_add_f32_e32 v0, v92, v0
	v_add_f32_e32 v0, v93, v0
	v_cvt_pk_bf16_f32 v206, v90, v91
	v_cvt_pk_bf16_f32 v207, v92, v93
	v_mfma_f32_32x32x16_bf16 v[130:145], v[114:117], v[174:177], v[130:145]
	ds_read_b64_tr_b16 v[220:221], v129 offset:46592
	v_add_f32_e32 v0, v94, v0
	v_add_f32_e32 v0, v95, v0
	v_add_f32_e32 v0, v96, v0
	v_add_f32_e32 v0, v97, v0
	v_add_f32_e32 v127, v127, v0
	v_cvt_pk_bf16_f32 v208, v94, v95
	v_cvt_pk_bf16_f32 v209, v96, v97
	s_waitcnt lgkmcnt(6)
	v_mfma_f32_32x32x16_bf16 v[2:17], v[190:193], v[210:213], v[2:17]
	v_add_u32_e32 v129, s44, v202
	v_exp_f32_e32 v98, v98
	v_exp_f32_e32 v99, v99
	v_exp_f32_e32 v100, v100
	v_exp_f32_e32 v101, v101
	s_waitcnt lgkmcnt(4)
	v_mfma_f32_32x32x16_bf16 v[18:33], v[190:193], v[118:121], v[18:33]
	ds_read_b128 v[178:181], v129
	v_exp_f32_e32 v102, v102
	v_exp_f32_e32 v103, v103
	v_exp_f32_e32 v104, v104
	v_exp_f32_e32 v105, v105
	s_add_i32 s10, s51, s39
	s_mov_b32 m0, s10
	s_nop 0
	global_load_lds_dwordx4 v215, s[36:37]
	s_add_i32 s10, s10, 0x1000
	s_mov_b32 m0, s10
	s_nop 0
	global_load_lds_dwordx4 v204, s[36:37]
	s_add_u32 s36, s36, 0x30000
	s_addc_u32 s37, s37, 0
	v_mfma_f32_32x32x16_bf16 v[34:49], v[198:201], v[210:213], v[34:49]
	ds_read_b128 v[182:185], v129 offset:2048
	v_exp_f32_e32 v106, v106
	v_exp_f32_e32 v107, v107
	v_exp_f32_e32 v108, v108
	v_exp_f32_e32 v109, v109
	v_mfma_f32_32x32x16_bf16 v[50:65], v[198:201], v[118:121], v[50:65]
	ds_read_b128 v[186:189], v129 offset:4096
	v_exp_f32_e32 v110, v110
	v_exp_f32_e32 v111, v111
	v_exp_f32_e32 v112, v112
	v_exp_f32_e32 v113, v113
	s_waitcnt lgkmcnt(5)
	v_mfma_f32_32x32x16_bf16 v[2:17], v[194:197], v[122:125], v[2:17]
	ds_read_b128 v[114:117], v129 offset:6144
	v_exp_f32_e32 v130, v130
	v_exp_f32_e32 v131, v131
	v_exp_f32_e32 v132, v132
	v_exp_f32_e32 v133, v133
	s_waitcnt lgkmcnt(4)
	v_mfma_f32_32x32x16_bf16 v[18:33], v[194:197], v[218:221], v[18:33]
	v_exp_f32_e32 v134, v134
	v_exp_f32_e32 v135, v135
	v_exp_f32_e32 v136, v136
	v_exp_f32_e32 v137, v137
	v_mfma_f32_32x32x16_bf16 v[34:49], v[206:209], v[122:125], v[34:49]
	v_exp_f32_e32 v138, v138
	v_exp_f32_e32 v139, v139
	v_exp_f32_e32 v140, v140
	v_exp_f32_e32 v141, v141
	v_mfma_f32_32x32x16_bf16 v[50:65], v[206:209], v[218:221], v[50:65]
	v_exp_f32_e32 v142, v142
	v_exp_f32_e32 v143, v143
	v_exp_f32_e32 v144, v144
	v_exp_f32_e32 v145, v145
	s_waitcnt lgkmcnt(3)
	v_mfma_f32_32x32x16_bf16 v[66:81], v[178:181], v[146:149], 0
	s_mov_b32 s15, s14
	s_mov_b32 s14, s44
	s_mov_b32 s44, s51
	s_add_i32 s10, s51, 0x2000
	s_cmpk_lg_u32 s51, 0x8000
	s_cselect_b32 s51, s10, 0
	s_waitcnt vmcnt(4) lgkmcnt(0)
	s_barrier
; #define WAIT_BAR(N) asm volatile("s_waitcnt vmcnt(" #N ") lgkmcnt(0)\n\ts_barrier":::"memory")
;   #define RESC() do{ if(resc){ asm volatile("s_waitcnt lgkmcnt(0)":::"memory"); \
;       _Pragma("unroll") for(int d_=0;d_<2;++d_) _Pragma("unroll") for(int r=0;r<16;++r)o[d_][r]*=wsf[crow(r,hi)]; } }while(0)
;   #define ROT() do{sl_prev=sl_cur;sl_cur=sl_next;sl_next=sl_n2;sl_n2=(sl_n2==(NSLOT-1)*SLOTB)?0:sl_n2+SLOTB;}while(0)
; template<int MODE,int THRL,bool NOMAX> __device__ __forceinline__ void attn_unit(const bf16*Qs,const bf16*__restrict__ Ks,const bf16*__restrict__ Vs,bf16*Os,int S,int q0,float sink2,float slope2,float*ssq,char*shm,int tid_in){
;     ...
;   for(;t+5<NT;t+=2){
;     STEP(pB0,pB1,pA0,pA1,t,true,true,true);     WAIT_BAR(2); RESC(); ROT();
;     STEP(pA0,pA1,pB0,pB1,t+1,true,true,true);   RESC(); ROT();
;   }
	v_add_u32_e32 v129, s15, v217
	ds_read_b64_tr_b16 v[210:211], v129 offset:40960
	v_add_f32_e32 v0, v98, v99
	v_add_f32_e32 v0, v100, v0
	v_add_f32_e32 v0, v101, v0
	v_cvt_pk_bf16_f32 v190, v98, v99
	v_cvt_pk_bf16_f32 v191, v100, v101
	v_mfma_f32_32x32x16_bf16 v[82:97], v[178:181], v[162:165], 0
	ds_read_b64_tr_b16 v[212:213], v129 offset:41472
	v_add_f32_e32 v0, v102, v0
	v_add_f32_e32 v0, v103, v0
	v_add_f32_e32 v0, v104, v0
	v_add_f32_e32 v0, v105, v0
	v_cvt_pk_bf16_f32 v192, v102, v103
	v_cvt_pk_bf16_f32 v193, v104, v105
	s_add_i32 s10, s15, s38
	s_mov_b32 m0, s10
	s_nop 0
	global_load_lds_dwordx4 v214, s[28:29]
	s_add_i32 s10, s10, 0x1000
	s_mov_b32 m0, s10
	s_nop 0
	global_load_lds_dwordx4 v203, s[28:29]
	s_add_u32 s28, s28, 0x30000
	s_addc_u32 s29, s29, 0
	s_waitcnt lgkmcnt(4)
	v_mfma_f32_32x32x16_bf16 v[66:81], v[182:185], v[150:153], v[66:81]
	ds_read_b64_tr_b16 v[118:119], v129 offset:45056
	v_add_f32_e32 v0, v106, v0
	v_add_f32_e32 v0, v107, v0
	v_add_f32_e32 v0, v108, v0
	v_add_f32_e32 v0, v109, v0
	v_cvt_pk_bf16_f32 v194, v106, v107
	v_cvt_pk_bf16_f32 v195, v108, v109
	v_mfma_f32_32x32x16_bf16 v[82:97], v[182:185], v[166:169], v[82:97]
	ds_read_b64_tr_b16 v[120:121], v129 offset:45568
	v_add_f32_e32 v0, v110, v0
	v_add_f32_e32 v0, v111, v0
	v_add_f32_e32 v0, v112, v0
	v_add_f32_e32 v0, v113, v0
	v_add_f32_e32 v126, v126, v0
	v_cvt_pk_bf16_f32 v196, v110, v111
	v_cvt_pk_bf16_f32 v197, v112, v113
	s_waitcnt lgkmcnt(5)
	v_mfma_f32_32x32x16_bf16 v[66:81], v[186:189], v[154:157], v[66:81]
	ds_read_b64_tr_b16 v[122:123], v129 offset:41984
	v_add_f32_e32 v0, v130, v131
	v_add_f32_e32 v0, v132, v0
	v_add_f32_e32 v0, v133, v0
	v_cvt_pk_bf16_f32 v198, v130, v131
	v_cvt_pk_bf16_f32 v199, v132, v133
	v_mfma_f32_32x32x16_bf16 v[82:97], v[186:189], v[170:173], v[82:97]
	ds_read_b64_tr_b16 v[124:125], v129 offset:42496
	v_add_f32_e32 v0, v134, v0
	v_add_f32_e32 v0, v135, v0
	v_add_f32_e32 v0, v136, v0
	v_add_f32_e32 v0, v137, v0
	v_cvt_pk_bf16_f32 v200, v134, v135
	v_cvt_pk_bf16_f32 v201, v136, v137
	s_waitcnt lgkmcnt(6)
	v_mfma_f32_32x32x16_bf16 v[66:81], v[114:117], v[158:161], v[66:81]
	ds_read_b64_tr_b16 v[218:219], v129 offset:46080
	v_add_f32_e32 v0, v138, v0
	v_add_f32_e32 v0, v139, v0
	v_add_f32_e32 v0, v140, v0
	v_add_f32_e32 v0, v141, v0
	v_cvt_pk_bf16_f32 v206, v138, v139
	v_cvt_pk_bf16_f32 v207, v140, v141
	v_mfma_f32_32x32x16_bf16 v[82:97], v[114:117], v[174:177], v[82:97]
	ds_read_b64_tr_b16 v[220:221], v129 offset:46592
	v_add_f32_e32 v0, v142, v0
	v_add_f32_e32 v0, v143, v0
	v_add_f32_e32 v0, v144, v0
	v_add_f32_e32 v0, v145, v0
	v_add_f32_e32 v127, v127, v0
	v_cvt_pk_bf16_f32 v208, v142, v143
	v_cvt_pk_bf16_f32 v209, v144, v145
	s_waitcnt lgkmcnt(6)
	v_mfma_f32_32x32x16_bf16 v[2:17], v[190:193], v[210:213], v[2:17]
	v_add_u32_e32 v129, s44, v202
	v_exp_f32_e32 v66, v66
	v_exp_f32_e32 v67, v67
	v_exp_f32_e32 v68, v68
	v_exp_f32_e32 v69, v69
	s_waitcnt lgkmcnt(4)
	v_mfma_f32_32x32x16_bf16 v[18:33], v[190:193], v[118:121], v[18:33]
	ds_read_b128 v[178:181], v129
	v_exp_f32_e32 v70, v70
	v_exp_f32_e32 v71, v71
	v_exp_f32_e32 v72, v72
	v_exp_f32_e32 v73, v73
	s_add_i32 s10, s51, s39
	s_mov_b32 m0, s10
	s_nop 0
	global_load_lds_dwordx4 v215, s[36:37]
	s_add_i32 s10, s10, 0x1000
	s_mov_b32 m0, s10
	s_nop 0
	global_load_lds_dwordx4 v204, s[36:37]
	s_add_u32 s36, s36, 0x30000
	s_addc_u32 s37, s37, 0
	v_mfma_f32_32x32x16_bf16 v[34:49], v[198:201], v[210:213], v[34:49]
	ds_read_b128 v[182:185], v129 offset:2048
	v_exp_f32_e32 v74, v74
	v_exp_f32_e32 v75, v75
	v_exp_f32_e32 v76, v76
	v_exp_f32_e32 v77, v77
	v_mfma_f32_32x32x16_bf16 v[50:65], v[198:201], v[118:121], v[50:65]
	ds_read_b128 v[186:189], v129 offset:4096
	v_exp_f32_e32 v78, v78
	v_exp_f32_e32 v79, v79
	v_exp_f32_e32 v80, v80
	v_exp_f32_e32 v81, v81
	s_waitcnt lgkmcnt(5)
	v_mfma_f32_32x32x16_bf16 v[2:17], v[194:197], v[122:125], v[2:17]
	ds_read_b128 v[114:117], v129 offset:6144
	v_exp_f32_e32 v82, v82
	v_exp_f32_e32 v83, v83
	v_exp_f32_e32 v84, v84
	v_exp_f32_e32 v85, v85
	s_waitcnt lgkmcnt(4)
	v_mfma_f32_32x32x16_bf16 v[18:33], v[194:197], v[218:221], v[18:33]
	v_exp_f32_e32 v86, v86
	v_exp_f32_e32 v87, v87
	v_exp_f32_e32 v88, v88
	v_exp_f32_e32 v89, v89
	v_mfma_f32_32x32x16_bf16 v[34:49], v[206:209], v[122:125], v[34:49]
	v_exp_f32_e32 v90, v90
	v_exp_f32_e32 v91, v91
	v_exp_f32_e32 v92, v92
	v_exp_f32_e32 v93, v93
	v_mfma_f32_32x32x16_bf16 v[50:65], v[206:209], v[218:221], v[50:65]
	v_exp_f32_e32 v94, v94
	v_exp_f32_e32 v95, v95
	v_exp_f32_e32 v96, v96
	v_exp_f32_e32 v97, v97
	s_waitcnt lgkmcnt(3)
	v_mfma_f32_32x32x16_bf16 v[98:113], v[178:181], v[146:149], 0
	s_mov_b32 s15, s14
	s_mov_b32 s14, s44
	s_mov_b32 s44, s51
	s_add_i32 s10, s51, 0x2000
	s_cmpk_lg_u32 s51, 0x8000
	s_cselect_b32 s51, s10, 0
	s_add_i32 s18, s18, 2
	s_add_i32 s10, s18, 1
	s_cmp_lt_u32 s10, s40
	s_cbranch_scc1 .Lkvs_loopA
; #define WAIT_BAR(N) asm volatile("s_waitcnt vmcnt(" #N ") lgkmcnt(0)\n\ts_barrier":::"memory")
;   #define RESC() do{ if(resc){ asm volatile("s_waitcnt lgkmcnt(0)":::"memory"); \
;       _Pragma("unroll") for(int d_=0;d_<2;++d_) _Pragma("unroll") for(int r=0;r<16;++r)o[d_][r]*=wsf[crow(r,hi)]; } }while(0)
;   #define ROT() do{sl_prev=sl_cur;sl_cur=sl_next;sl_next=sl_n2;sl_n2=(sl_n2==(NSLOT-1)*SLOTB)?0:sl_n2+SLOTB;}while(0)
;   #define ENDW(tt) do{ if((tt)+4<NT){WAIT_BAR(2);} else if((tt)+2<NT){WAIT_BAR(1);} else {WAIT_BAR(0);} }while(0)
; template<int MODE,int THRL,bool NOMAX> __device__ __forceinline__ void attn_unit(const bf16*Qs,const bf16*__restrict__ Ks,const bf16*__restrict__ Vs,bf16*Os,int S,int q0,float sink2,float slope2,float*ssq,char*shm,int tid_in){
;     ...
;   for(;t+1<NT;t+=2){
;     STEP(pB0,pB1,pA0,pA1,t,(t+4<NT),(t+2<NT),(t+1<NT));       ENDW(t);   RESC(); ROT();
;     STEP(pA0,pA1,pB0,pB1,t+1,(t+5<NT),(t+3<NT),(t+2<NT));     if(t+3>=NT){WAIT_BAR(0);} RESC(); ROT();
;   }
;   STEP(pB0,pB1,pA0,pA1,NT-1,false,false,false); RESC();
	v_add_u32_e32 v129, s15, v217
	ds_read_b64_tr_b16 v[210:211], v129 offset:40960
	v_add_f32_e32 v0, v66, v67
	v_add_f32_e32 v0, v68, v0
	v_add_f32_e32 v0, v69, v0
	v_cvt_pk_bf16_f32 v190, v66, v67
	v_cvt_pk_bf16_f32 v191, v68, v69
	v_mfma_f32_32x32x16_bf16 v[130:145], v[178:181], v[162:165], 0
	ds_read_b64_tr_b16 v[212:213], v129 offset:41472
	v_add_f32_e32 v0, v70, v0
	v_add_f32_e32 v0, v71, v0
	v_add_f32_e32 v0, v72, v0
	v_add_f32_e32 v0, v73, v0
	v_cvt_pk_bf16_f32 v192, v70, v71
	v_cvt_pk_bf16_f32 v193, v72, v73
	s_waitcnt lgkmcnt(4)
	v_mfma_f32_32x32x16_bf16 v[98:113], v[182:185], v[150:153], v[98:113]
	ds_read_b64_tr_b16 v[118:119], v129 offset:45056
	v_add_f32_e32 v0, v74, v0
	v_add_f32_e32 v0, v75, v0
	v_add_f32_e32 v0, v76, v0
	v_add_f32_e32 v0, v77, v0
	v_cvt_pk_bf16_f32 v194, v74, v75
	v_cvt_pk_bf16_f32 v195, v76, v77
	v_mfma_f32_32x32x16_bf16 v[130:145], v[182:185], v[166:169], v[130:145]
	ds_read_b64_tr_b16 v[120:121], v129 offset:45568
	v_add_f32_e32 v0, v78, v0
	v_add_f32_e32 v0, v79, v0
	v_add_f32_e32 v0, v80, v0
	v_add_f32_e32 v0, v81, v0
	v_add_f32_e32 v126, v126, v0
	v_cvt_pk_bf16_f32 v196, v78, v79
	v_cvt_pk_bf16_f32 v197, v80, v81
	s_waitcnt lgkmcnt(5)
	v_mfma_f32_32x32x16_bf16 v[98:113], v[186:189], v[154:157], v[98:113]
	ds_read_b64_tr_b16 v[122:123], v129 offset:41984
	v_add_f32_e32 v0, v82, v83
	v_add_f32_e32 v0, v84, v0
	v_add_f32_e32 v0, v85, v0
	v_cvt_pk_bf16_f32 v198, v82, v83
	v_cvt_pk_bf16_f32 v199, v84, v85
	v_mfma_f32_32x32x16_bf16 v[130:145], v[186:189], v[170:173], v[130:145]
	ds_read_b64_tr_b16 v[124:125], v129 offset:42496
	v_add_f32_e32 v0, v86, v0
	v_add_f32_e32 v0, v87, v0
	v_add_f32_e32 v0, v88, v0
	v_add_f32_e32 v0, v89, v0
	v_cvt_pk_bf16_f32 v200, v86, v87
	v_cvt_pk_bf16_f32 v201, v88, v89
	s_waitcnt lgkmcnt(6)
	v_mfma_f32_32x32x16_bf16 v[98:113], v[114:117], v[158:161], v[98:113]
	ds_read_b64_tr_b16 v[218:219], v129 offset:46080
	v_add_f32_e32 v0, v90, v0
	v_add_f32_e32 v0, v91, v0
	v_add_f32_e32 v0, v92, v0
	v_add_f32_e32 v0, v93, v0
	v_cvt_pk_bf16_f32 v206, v90, v91
	v_cvt_pk_bf16_f32 v207, v92, v93
	v_mfma_f32_32x32x16_bf16 v[130:145], v[114:117], v[174:177], v[130:145]
	ds_read_b64_tr_b16 v[220:221], v129 offset:46592
	v_add_f32_e32 v0, v94, v0
	v_add_f32_e32 v0, v95, v0
	v_add_f32_e32 v0, v96, v0
	v_add_f32_e32 v0, v97, v0
	v_add_f32_e32 v127, v127, v0
	v_cvt_pk_bf16_f32 v208, v94, v95
	v_cvt_pk_bf16_f32 v209, v96, v97
	s_waitcnt lgkmcnt(6)
	v_mfma_f32_32x32x16_bf16 v[2:17], v[190:193], v[210:213], v[2:17]
	v_add_u32_e32 v129, s44, v202
	v_exp_f32_e32 v98, v98
	v_exp_f32_e32 v99, v99
	v_exp_f32_e32 v100, v100
	v_exp_f32_e32 v101, v101
	s_waitcnt lgkmcnt(4)
	v_mfma_f32_32x32x16_bf16 v[18:33], v[190:193], v[118:121], v[18:33]
	ds_read_b128 v[178:181], v129
	v_exp_f32_e32 v102, v102
	v_exp_f32_e32 v103, v103
	v_exp_f32_e32 v104, v104
	v_exp_f32_e32 v105, v105
	v_mfma_f32_32x32x16_bf16 v[34:49], v[198:201], v[210:213], v[34:49]
	ds_read_b128 v[182:185], v129 offset:2048
	v_exp_f32_e32 v106, v106
	v_exp_f32_e32 v107, v107
	v_exp_f32_e32 v108, v108
	v_exp_f32_e32 v109, v109
	v_mfma_f32_32x32x16_bf16 v[50:65], v[198:201], v[118:121], v[50:65]
	ds_read_b128 v[186:189], v129 offset:4096
	v_exp_f32_e32 v110, v110
	v_exp_f32_e32 v111, v111
	v_exp_f32_e32 v112, v112
	v_exp_f32_e32 v113, v113
	s_waitcnt lgkmcnt(5)
	v_mfma_f32_32x32x16_bf16 v[2:17], v[194:197], v[122:125], v[2:17]
	ds_read_b128 v[114:117], v129 offset:6144
	v_exp_f32_e32 v130, v130
	v_exp_f32_e32 v131, v131
	v_exp_f32_e32 v132, v132
	v_exp_f32_e32 v133, v133
	s_waitcnt lgkmcnt(4)
	v_mfma_f32_32x32x16_bf16 v[18:33], v[194:197], v[218:221], v[18:33]
	v_exp_f32_e32 v134, v134
	v_exp_f32_e32 v135, v135
	v_exp_f32_e32 v136, v136
	v_exp_f32_e32 v137, v137
	v_mfma_f32_32x32x16_bf16 v[34:49], v[206:209], v[122:125], v[34:49]
	v_exp_f32_e32 v138, v138
	v_exp_f32_e32 v139, v139
	v_exp_f32_e32 v140, v140
	v_exp_f32_e32 v141, v141
	v_mfma_f32_32x32x16_bf16 v[50:65], v[206:209], v[218:221], v[50:65]
	v_exp_f32_e32 v142, v142
	v_exp_f32_e32 v143, v143
	v_exp_f32_e32 v144, v144
	v_exp_f32_e32 v145, v145
	s_mov_b32 s15, s14
	s_mov_b32 s14, s44
	s_mov_b32 s44, s51
	s_add_i32 s10, s51, 0x2000
	s_cmpk_lg_u32 s51, 0x8000
	s_cselect_b32 s51, s10, 0
	s_waitcnt vmcnt(0) lgkmcnt(0)
	s_barrier
; #define SBAR() __builtin_amdgcn_sched_barrier(0)
;   #define PKW(P,B) cvtpk_s(P[B],P[B+1])
;   #define LSUM(k) do{ if(LSM){ lsum=__builtin_amdgcn_mfma_f32_32x32x16_bf16(PAF(k),onesv,lsum,0,0,0); SBAR(); } }while(0)
; template<int MODE,int THRL,bool NOMAX> __device__ __forceinline__ void attn_unit(const bf16*Qs,const bf16*__restrict__ Ks,const bf16*__restrict__ Vs,bf16*Os,int S,int q0,float sink2,float slope2,float*ssq,char*shm,int tid_in){
;     ...
;   { float sacc=pB0[0]+pB0[1]; _Pragma("unroll") for(int r=2;r<16;++r)sacc+=pB0[r]; _Pragma("unroll") for(int r=0;r<16;++r)sacc+=pB1[r]; l_reg+=sacc;
;     pw0=(u32x4){PKW(pB0,0),PKW(pB0,2),PKW(pB0,4),PKW(pB0,6)};pw1=(u32x4){PKW(pB0,8),PKW(pB0,10),PKW(pB0,12),PKW(pB0,14)};pw2=(u32x4){PKW(pB1,0),PKW(pB1,2),PKW(pB1,4),PKW(pB1,6)};pw3=(u32x4){PKW(pB1,8),PKW(pB1,10),PKW(pB1,12),PKW(pB1,14)};
;     SBAR(); pv(o,vb0+sl_cur,PAF(0),PAF(1),PAF(2),PAF(3)); LSUM(0); LSUM(1); LSUM(2); LSUM(3); }
.Lkvs_drain:
	v_add_u32_e32 v129, s15, v217
	ds_read_b64_tr_b16 v[210:211], v129 offset:40960
	ds_read_b64_tr_b16 v[212:213], v129 offset:41472
	ds_read_b64_tr_b16 v[118:119], v129 offset:45056
	ds_read_b64_tr_b16 v[120:121], v129 offset:45568
	ds_read_b64_tr_b16 v[122:123], v129 offset:41984
	ds_read_b64_tr_b16 v[124:125], v129 offset:42496
	ds_read_b64_tr_b16 v[218:219], v129 offset:46080
	ds_read_b64_tr_b16 v[220:221], v129 offset:46592
	v_add_f32_e32 v0, v98, v99
	v_add_f32_e32 v0, v100, v0
	v_add_f32_e32 v0, v101, v0
	v_add_f32_e32 v0, v102, v0
	v_add_f32_e32 v0, v103, v0
	v_add_f32_e32 v0, v104, v0
	v_add_f32_e32 v0, v105, v0
	v_add_f32_e32 v0, v106, v0
	v_add_f32_e32 v0, v107, v0
	v_add_f32_e32 v0, v108, v0
	v_add_f32_e32 v0, v109, v0
	v_add_f32_e32 v0, v110, v0
	v_add_f32_e32 v0, v111, v0
	v_add_f32_e32 v0, v112, v0
	v_add_f32_e32 v0, v113, v0
	v_add_f32_e32 v126, v126, v0
	v_cvt_pk_bf16_f32 v190, v98, v99
	v_cvt_pk_bf16_f32 v191, v100, v101
	v_cvt_pk_bf16_f32 v192, v102, v103
	v_cvt_pk_bf16_f32 v193, v104, v105
	v_cvt_pk_bf16_f32 v194, v106, v107
	v_cvt_pk_bf16_f32 v195, v108, v109
	v_cvt_pk_bf16_f32 v196, v110, v111
	v_cvt_pk_bf16_f32 v197, v112, v113
	v_add_f32_e32 v0, v130, v131
	v_add_f32_e32 v0, v132, v0
	v_add_f32_e32 v0, v133, v0
	v_add_f32_e32 v0, v134, v0
	v_add_f32_e32 v0, v135, v0
	v_add_f32_e32 v0, v136, v0
	v_add_f32_e32 v0, v137, v0
	v_add_f32_e32 v0, v138, v0
	v_add_f32_e32 v0, v139, v0
	v_add_f32_e32 v0, v140, v0
	v_add_f32_e32 v0, v141, v0
	v_add_f32_e32 v0, v142, v0
	v_add_f32_e32 v0, v143, v0
	v_add_f32_e32 v0, v144, v0
	v_add_f32_e32 v0, v145, v0
	v_add_f32_e32 v127, v127, v0
	v_cvt_pk_bf16_f32 v198, v130, v131
	v_cvt_pk_bf16_f32 v199, v132, v133
	v_cvt_pk_bf16_f32 v200, v134, v135
	v_cvt_pk_bf16_f32 v201, v136, v137
	v_cvt_pk_bf16_f32 v206, v138, v139
	v_cvt_pk_bf16_f32 v207, v140, v141
	v_cvt_pk_bf16_f32 v208, v142, v143
	v_cvt_pk_bf16_f32 v209, v144, v145
	s_nop 1
	s_waitcnt lgkmcnt(6)
	v_mfma_f32_32x32x16_bf16 v[2:17], v[190:193], v[210:213], v[2:17]
	s_waitcnt lgkmcnt(4)
	v_mfma_f32_32x32x16_bf16 v[18:33], v[190:193], v[118:121], v[18:33]
	v_mfma_f32_32x32x16_bf16 v[34:49], v[198:201], v[210:213], v[34:49]
	v_mfma_f32_32x32x16_bf16 v[50:65], v[198:201], v[118:121], v[50:65]
	s_waitcnt lgkmcnt(2)
	v_mfma_f32_32x32x16_bf16 v[2:17], v[194:197], v[122:125], v[2:17]
	s_waitcnt lgkmcnt(0)
	v_mfma_f32_32x32x16_bf16 v[18:33], v[194:197], v[218:221], v[18:33]
	v_mfma_f32_32x32x16_bf16 v[34:49], v[206:209], v[122:125], v[34:49]
	v_mfma_f32_32x32x16_bf16 v[50:65], v[206:209], v[218:221], v[50:65]
	s_waitcnt vmcnt(0) lgkmcnt(0)
	s_barrier
	v_and_b32_e32 v129, 63, v251
	v_lshlrev_b32_e32 v129, 2, v129
	s_xor_b32 s10, s30, 4
	s_lshl_b32 s11, s10, 13
	v_add_u32_e32 v186, s11, v129
	s_lshl_b32 s11, s10, 8
	s_add_i32 s11, s11, 0x10000
	v_add_u32_e32 v187, s11, v129
	s_lshl_b32 s11, s30, 13
	v_add_u32_e32 v114, s11, v129
	s_lshl_b32 s11, s30, 8
	s_add_i32 s11, s11, 0x10000
	v_add_u32_e32 v115, s11, v129
	s_cmp_eq_u32 s57, 0
	s_cbranch_scc1 .Lkvs_fin0
	ds_write_b32 v186, v2 offset:0
	ds_write_b32 v186, v3 offset:256
	ds_write_b32 v186, v4 offset:512
	ds_write_b32 v186, v5 offset:768
	ds_write_b32 v186, v6 offset:1024
	ds_write_b32 v186, v7 offset:1280
	ds_write_b32 v186, v8 offset:1536
	ds_write_b32 v186, v9 offset:1792
	ds_write_b32 v186, v10 offset:2048
	ds_write_b32 v186, v11 offset:2304
	ds_write_b32 v186, v12 offset:2560
	ds_write_b32 v186, v13 offset:2816
	ds_write_b32 v186, v14 offset:3072
	ds_write_b32 v186, v15 offset:3328
	ds_write_b32 v186, v16 offset:3584
	ds_write_b32 v186, v17 offset:3840
	ds_write_b32 v186, v18 offset:4096
	ds_write_b32 v186, v19 offset:4352
	ds_write_b32 v186, v20 offset:4608
	ds_write_b32 v186, v21 offset:4864
	ds_write_b32 v186, v22 offset:5120
	ds_write_b32 v186, v23 offset:5376
	ds_write_b32 v186, v24 offset:5632
	ds_write_b32 v186, v25 offset:5888
	ds_write_b32 v186, v26 offset:6144
	ds_write_b32 v186, v27 offset:6400
	ds_write_b32 v186, v28 offset:6656
	ds_write_b32 v186, v29 offset:6912
	ds_write_b32 v186, v30 offset:7168
	ds_write_b32 v186, v31 offset:7424
	ds_write_b32 v186, v32 offset:7680
	ds_write_b32 v186, v33 offset:7936
	ds_write_b32 v187, v126
	s_waitcnt lgkmcnt(0)
	s_barrier
	ds_read_b32 v66, v114 offset:0
	ds_read_b32 v67, v114 offset:256
	ds_read_b32 v68, v114 offset:512
	ds_read_b32 v69, v114 offset:768
	ds_read_b32 v70, v114 offset:1024
	ds_read_b32 v71, v114 offset:1280
	ds_read_b32 v72, v114 offset:1536
	ds_read_b32 v73, v114 offset:1792
	ds_read_b32 v74, v114 offset:2048
	ds_read_b32 v75, v114 offset:2304
	ds_read_b32 v76, v114 offset:2560
	ds_read_b32 v77, v114 offset:2816
	ds_read_b32 v78, v114 offset:3072
	ds_read_b32 v79, v114 offset:3328
	ds_read_b32 v80, v114 offset:3584
	ds_read_b32 v81, v114 offset:3840
	ds_read_b32 v82, v114 offset:4096
	ds_read_b32 v83, v114 offset:4352
	ds_read_b32 v84, v114 offset:4608
	ds_read_b32 v85, v114 offset:4864
	ds_read_b32 v86, v114 offset:5120
	ds_read_b32 v87, v114 offset:5376
	ds_read_b32 v88, v114 offset:5632
	ds_read_b32 v89, v114 offset:5888
	ds_read_b32 v90, v114 offset:6144
	ds_read_b32 v91, v114 offset:6400
	ds_read_b32 v92, v114 offset:6656
	ds_read_b32 v93, v114 offset:6912
	ds_read_b32 v94, v114 offset:7168
	ds_read_b32 v95, v114 offset:7424
	ds_read_b32 v96, v114 offset:7680
	ds_read_b32 v97, v114 offset:7936
	ds_read_b32 v178, v115
	s_waitcnt lgkmcnt(0)
; __device__ __forceinline__ int crow(int r,int hi){return (r&3)+8*(r>>2)+4*hi;}
; template<int MODE,int THRL,bool NOMAX> __device__ __forceinline__ void attn_unit(const bf16*Qs,const bf16*__restrict__ Ks,const bf16*__restrict__ Vs,bf16*Os,int S,int q0,float sink2,float slope2,float*ssq,char*shm,int tid_in){
;     ...
;   {auto rr=__builtin_amdgcn_permlane32_swap(__float_as_uint(l_reg),__float_as_uint(l_reg),false,false);l_reg=__uint_as_float(rr[0])+__uint_as_float(rr[1]);}
;   if(hi==0)wsf[32+r32]=l_reg;asm volatile("s_waitcnt lgkmcnt(0)":::"memory");
;   float rli[16];
;   #pragma unroll
;   for(int r=0;r<16;++r)rli[r]=LSM?__builtin_amdgcn_rcpf(lsum[r]):__builtin_amdgcn_rcpf(wsf[32+crow(r,hi)]);
;     ...
;   bf16*Ow=Os+(long)(q0+wid*QBLK)*OPITCH;
;   { bf16*stg=(bf16*)(shm+LDS_OST)+wid*2048;
;     #pragma unroll
;     for(int r=0;r<16;++r){const int orow=crow(r,hi);
;       #pragma unroll
;       for(int d0=0;d0<2;++d0)stg[orow*64+d0*32+r32]=__float2bfloat16(o[d0][r]*rli[r]);}
	v_add_f32_e32 v34, v34, v66
	v_add_f32_e32 v35, v35, v67
	v_add_f32_e32 v36, v36, v68
	v_add_f32_e32 v37, v37, v69
	v_add_f32_e32 v38, v38, v70
	v_add_f32_e32 v39, v39, v71
	v_add_f32_e32 v40, v40, v72
	v_add_f32_e32 v41, v41, v73
	v_add_f32_e32 v42, v42, v74
	v_add_f32_e32 v43, v43, v75
	v_add_f32_e32 v44, v44, v76
	v_add_f32_e32 v45, v45, v77
	v_add_f32_e32 v46, v46, v78
	v_add_f32_e32 v47, v47, v79
	v_add_f32_e32 v48, v48, v80
	v_add_f32_e32 v49, v49, v81
	v_add_f32_e32 v50, v50, v82
	v_add_f32_e32 v51, v51, v83
	v_add_f32_e32 v52, v52, v84
	v_add_f32_e32 v53, v53, v85
	v_add_f32_e32 v54, v54, v86
	v_add_f32_e32 v55, v55, v87
	v_add_f32_e32 v56, v56, v88
	v_add_f32_e32 v57, v57, v89
	v_add_f32_e32 v58, v58, v90
	v_add_f32_e32 v59, v59, v91
	v_add_f32_e32 v60, v60, v92
	v_add_f32_e32 v61, v61, v93
	v_add_f32_e32 v62, v62, v94
	v_add_f32_e32 v63, v63, v95
	v_add_f32_e32 v64, v64, v96
	v_add_f32_e32 v65, v65, v97
	v_add_f32_e32 v127, v127, v178
	v_and_b32_e32 v66, 31, v251
	v_and_b32_e32 v67, 63, v251
	v_lshrrev_b32_e32 v67, 5, v67
	s_lshl_b32 s10, s30, 8
	s_add_i32 s10, s10, 0x14000
	s_lshl_b32 s11, s30, 12
	s_add_i32 s11, s11, 0x14800
	v_and_b32_e32 v74, 63, v251
	v_lshrrev_b32_e32 v75, 3, v74
	v_and_b32_e32 v74, 7, v74
	v_lshlrev_b32_e32 v76, 4, v74
	v_lshl_add_u32 v76, v75, 7, v76
	v_add_u32_e32 v76, s11, v76
	v_lshlrev_b32_e32 v69, 9, v67
	v_lshl_add_u32 v69, v66, 1, v69
	v_add_u32_e32 v69, s11, v69
	v_lshl_add_u32 v68, v66, 2, s10
	v_mov_b32_e32 v70, v127
	s_nop 1
	v_permlane32_swap_b32_e32 v127, v70
	s_nop 1
	v_add_f32_e32 v70, v127, v70
	ds_write_b32 v68, v70 offset:128
	v_lshl_add_u32 v71, v67, 4, s10
	s_waitcnt lgkmcnt(0)
	ds_read_b128 v[82:85], v71 offset:128
	ds_read_b128 v[86:89], v71 offset:160
	ds_read_b128 v[90:93], v71 offset:192
	ds_read_b128 v[94:97], v71 offset:224
	s_waitcnt lgkmcnt(0)
	v_rcp_f32_e32 v82, v82
	v_rcp_f32_e32 v83, v83
	v_rcp_f32_e32 v84, v84
	v_rcp_f32_e32 v85, v85
	v_rcp_f32_e32 v86, v86
	v_rcp_f32_e32 v87, v87
	v_rcp_f32_e32 v88, v88
	v_rcp_f32_e32 v89, v89
	v_rcp_f32_e32 v90, v90
	v_rcp_f32_e32 v91, v91
	v_rcp_f32_e32 v92, v92
	v_rcp_f32_e32 v93, v93
	v_rcp_f32_e32 v94, v94
	v_rcp_f32_e32 v95, v95
	v_rcp_f32_e32 v96, v96
	v_rcp_f32_e32 v97, v97
	s_nop 0
	v_mul_f32_e32 v72, v34, v82
	v_cvt_pk_bf16_f32 v72, v72, v72
	ds_write_b16 v69, v72 offset:0
	v_mul_f32_e32 v73, v50, v82
	v_cvt_pk_bf16_f32 v73, v73, v73
	ds_write_b16 v69, v73 offset:64
	v_mul_f32_e32 v72, v35, v83
	v_cvt_pk_bf16_f32 v72, v72, v72
	ds_write_b16 v69, v72 offset:128
	v_mul_f32_e32 v73, v51, v83
	v_cvt_pk_bf16_f32 v73, v73, v73
	ds_write_b16 v69, v73 offset:192
	v_mul_f32_e32 v72, v36, v84
	v_cvt_pk_bf16_f32 v72, v72, v72
	ds_write_b16 v69, v72 offset:256
	v_mul_f32_e32 v73, v52, v84
	v_cvt_pk_bf16_f32 v73, v73, v73
	ds_write_b16 v69, v73 offset:320
	v_mul_f32_e32 v72, v37, v85
	v_cvt_pk_bf16_f32 v72, v72, v72
	ds_write_b16 v69, v72 offset:384
	v_mul_f32_e32 v73, v53, v85
	v_cvt_pk_bf16_f32 v73, v73, v73
	ds_write_b16 v69, v73 offset:448
	v_mul_f32_e32 v72, v38, v86
	v_cvt_pk_bf16_f32 v72, v72, v72
	ds_write_b16 v69, v72 offset:1024
	v_mul_f32_e32 v73, v54, v86
	v_cvt_pk_bf16_f32 v73, v73, v73
	ds_write_b16 v69, v73 offset:1088
	v_mul_f32_e32 v72, v39, v87
	v_cvt_pk_bf16_f32 v72, v72, v72
	ds_write_b16 v69, v72 offset:1152
	v_mul_f32_e32 v73, v55, v87
	v_cvt_pk_bf16_f32 v73, v73, v73
	ds_write_b16 v69, v73 offset:1216
	v_mul_f32_e32 v72, v40, v88
	v_cvt_pk_bf16_f32 v72, v72, v72
	ds_write_b16 v69, v72 offset:1280
	v_mul_f32_e32 v73, v56, v88
	v_cvt_pk_bf16_f32 v73, v73, v73
	ds_write_b16 v69, v73 offset:1344
	v_mul_f32_e32 v72, v41, v89
	v_cvt_pk_bf16_f32 v72, v72, v72
	ds_write_b16 v69, v72 offset:1408
	v_mul_f32_e32 v73, v57, v89
	v_cvt_pk_bf16_f32 v73, v73, v73
	ds_write_b16 v69, v73 offset:1472
	v_mul_f32_e32 v72, v42, v90
	v_cvt_pk_bf16_f32 v72, v72, v72
	ds_write_b16 v69, v72 offset:2048
	v_mul_f32_e32 v73, v58, v90
	v_cvt_pk_bf16_f32 v73, v73, v73
	ds_write_b16 v69, v73 offset:2112
	v_mul_f32_e32 v72, v43, v91
	v_cvt_pk_bf16_f32 v72, v72, v72
	ds_write_b16 v69, v72 offset:2176
	v_mul_f32_e32 v73, v59, v91
	v_cvt_pk_bf16_f32 v73, v73, v73
	ds_write_b16 v69, v73 offset:2240
	v_mul_f32_e32 v72, v44, v92
	v_cvt_pk_bf16_f32 v72, v72, v72
	ds_write_b16 v69, v72 offset:2304
	v_mul_f32_e32 v73, v60, v92
	v_cvt_pk_bf16_f32 v73, v73, v73
	ds_write_b16 v69, v73 offset:2368
	v_mul_f32_e32 v72, v45, v93
	v_cvt_pk_bf16_f32 v72, v72, v72
	ds_write_b16 v69, v72 offset:2432
	v_mul_f32_e32 v73, v61, v93
	v_cvt_pk_bf16_f32 v73, v73, v73
	ds_write_b16 v69, v73 offset:2496
	v_mul_f32_e32 v72, v46, v94
	v_cvt_pk_bf16_f32 v72, v72, v72
	ds_write_b16 v69, v72 offset:3072
	v_mul_f32_e32 v73, v62, v94
	v_cvt_pk_bf16_f32 v73, v73, v73
	ds_write_b16 v69, v73 offset:3136
	v_mul_f32_e32 v72, v47, v95
	v_cvt_pk_bf16_f32 v72, v72, v72
	ds_write_b16 v69, v72 offset:3200
	v_mul_f32_e32 v73, v63, v95
	v_cvt_pk_bf16_f32 v73, v73, v73
	ds_write_b16 v69, v73 offset:3264
	v_mul_f32_e32 v72, v48, v96
	v_cvt_pk_bf16_f32 v72, v72, v72
	ds_write_b16 v69, v72 offset:3328
	v_mul_f32_e32 v73, v64, v96
	v_cvt_pk_bf16_f32 v73, v73, v73
	ds_write_b16 v69, v73 offset:3392
	v_mul_f32_e32 v72, v49, v97
	v_cvt_pk_bf16_f32 v72, v72, v72
	ds_write_b16 v69, v72 offset:3456
	v_mul_f32_e32 v73, v65, v97
	v_cvt_pk_bf16_f32 v73, v73, v73
	ds_write_b16 v69, v73 offset:3520
	s_add_i32 s14, s4, 32
	s_mul_i32 s18, s14, 0x800
	s_mul_hi_i32 s19, s14, 0x800
	s_add_u32 s18, s48, s18
	s_addc_u32 s19, s49, s19
	s_mul_i32 s44, s14, 64
	s_mul_hi_i32 s45, s14, 64
	s_add_u32 s44, s26, s44
	s_addc_u32 s45, s27, s45
	v_lshlrev_b32_e32 v78, 11, v75
	v_lshl_add_u32 v78, v74, 4, v78
	v_lshlrev_b32_e32 v77, 6, v75
	v_cmp_eq_u32_e32 vcc, 0, v74
	s_waitcnt lgkmcnt(0)
; #define lane ({ int l_ = (int)__builtin_amdgcn_mbcnt_hi(~0u, __builtin_amdgcn_mbcnt_lo(~0u, 0u)); asm volatile("" : "+v"(l_)); l_; })
; template<int MODE,int THRL,bool NOMAX> __device__ __forceinline__ void attn_unit(const bf16*Qs,const bf16*__restrict__ Ks,const bf16*__restrict__ Vs,bf16*Os,int S,int q0,float sink2,float slope2,float*ssq,char*shm,int tid_in){
;     ...
;     asm volatile("s_waitcnt lgkmcnt(0)":::"memory");
;     #pragma unroll
;     for(int i=0;i<4;++i){const int row=i*8+(lane>>3),ch=lane&7; const u32x4 v=*(const u32x4*)(stg+row*64+ch*8); ATTN_STORE16(Ow+(long)row*OPITCH+ch*8,v);
;       float sq=0.f;
;       #pragma unroll
;       for(int k=0;k<4;++k){const float a=__uint_as_float(v[k]<<16),b=__uint_as_float(v[k]&0xffff0000u); sq+=a*a+b*b;}
;       sq+=__shfl_xor(sq,1); sq+=__shfl_xor(sq,2); sq+=__shfl_xor(sq,4);
;       if(ch==0)ssq[(long)(q0+wid*QBLK+row)*16]=sq;} }
	ds_read_b128 v[98:101], v76 offset:0
	ds_read_b128 v[102:105], v76 offset:1024
	ds_read_b128 v[106:109], v76 offset:2048
	ds_read_b128 v[110:113], v76 offset:3072
	s_waitcnt lgkmcnt(3)
	global_store_dwordx4 v78, v[98:101], s[18:19] offset:0
	v_and_b32_e32 v72, 0xffff0000, v98
	v_lshlrev_b32_e32 v73, 16, v98
	v_mul_f32_e32 v72, v72, v72
	v_fmac_f32_e32 v72, v73, v73
	v_mov_b32_e32 v130, v72
	v_and_b32_e32 v72, 0xffff0000, v99
	v_lshlrev_b32_e32 v73, 16, v99
	v_mul_f32_e32 v72, v72, v72
	v_fmac_f32_e32 v72, v73, v73
	v_add_f32_e32 v130, v130, v72
	v_and_b32_e32 v72, 0xffff0000, v100
	v_lshlrev_b32_e32 v73, 16, v100
	v_mul_f32_e32 v72, v72, v72
	v_fmac_f32_e32 v72, v73, v73
	v_add_f32_e32 v130, v72, v130
	v_and_b32_e32 v72, 0xffff0000, v101
	v_lshlrev_b32_e32 v73, 16, v101
	v_mul_f32_e32 v72, v72, v72
	v_fmac_f32_e32 v72, v73, v73
	v_add_f32_e32 v130, v72, v130
	v_add_u32_e32 v78, 0x4000, v78
	s_waitcnt lgkmcnt(2)
	global_store_dwordx4 v78, v[102:105], s[18:19]
	v_and_b32_e32 v72, 0xffff0000, v102
	v_lshlrev_b32_e32 v73, 16, v102
	v_mul_f32_e32 v72, v72, v72
	v_fmac_f32_e32 v72, v73, v73
	v_mov_b32_e32 v131, v72
	v_and_b32_e32 v72, 0xffff0000, v103
	v_lshlrev_b32_e32 v73, 16, v103
	v_mul_f32_e32 v72, v72, v72
	v_fmac_f32_e32 v72, v73, v73
	v_add_f32_e32 v131, v131, v72
	v_and_b32_e32 v72, 0xffff0000, v104
	v_lshlrev_b32_e32 v73, 16, v104
	v_mul_f32_e32 v72, v72, v72
	v_fmac_f32_e32 v72, v73, v73
	v_add_f32_e32 v131, v72, v131
	v_and_b32_e32 v72, 0xffff0000, v105
	v_lshlrev_b32_e32 v73, 16, v105
	v_mul_f32_e32 v72, v72, v72
	v_fmac_f32_e32 v72, v73, v73
	v_add_f32_e32 v131, v72, v131
	v_add_u32_e32 v78, 0x4000, v78
	s_waitcnt lgkmcnt(1)
	global_store_dwordx4 v78, v[106:109], s[18:19]
	v_and_b32_e32 v72, 0xffff0000, v106
	v_lshlrev_b32_e32 v73, 16, v106
	v_mul_f32_e32 v72, v72, v72
	v_fmac_f32_e32 v72, v73, v73
	v_mov_b32_e32 v132, v72
	v_and_b32_e32 v72, 0xffff0000, v107
	v_lshlrev_b32_e32 v73, 16, v107
	v_mul_f32_e32 v72, v72, v72
	v_fmac_f32_e32 v72, v73, v73
	v_add_f32_e32 v132, v132, v72
	v_and_b32_e32 v72, 0xffff0000, v108
	v_lshlrev_b32_e32 v73, 16, v108
	v_mul_f32_e32 v72, v72, v72
	v_fmac_f32_e32 v72, v73, v73
	v_add_f32_e32 v132, v72, v132
	v_and_b32_e32 v72, 0xffff0000, v109
	v_lshlrev_b32_e32 v73, 16, v109
	v_mul_f32_e32 v72, v72, v72
	v_fmac_f32_e32 v72, v73, v73
	v_add_f32_e32 v132, v72, v132
	v_add_u32_e32 v78, 0x4000, v78
	s_waitcnt lgkmcnt(0)
	global_store_dwordx4 v78, v[110:113], s[18:19]
	v_and_b32_e32 v72, 0xffff0000, v110
	v_lshlrev_b32_e32 v73, 16, v110
	v_mul_f32_e32 v72, v72, v72
	v_fmac_f32_e32 v72, v73, v73
	v_mov_b32_e32 v133, v72
	v_and_b32_e32 v72, 0xffff0000, v111
	v_lshlrev_b32_e32 v73, 16, v111
	v_mul_f32_e32 v72, v72, v72
	v_fmac_f32_e32 v72, v73, v73
	v_add_f32_e32 v133, v133, v72
	v_and_b32_e32 v72, 0xffff0000, v112
	v_lshlrev_b32_e32 v73, 16, v112
	v_mul_f32_e32 v72, v72, v72
	v_fmac_f32_e32 v72, v73, v73
	v_add_f32_e32 v133, v72, v133
	v_and_b32_e32 v72, 0xffff0000, v113
	v_lshlrev_b32_e32 v73, 16, v113
	v_mul_f32_e32 v72, v72, v72
	v_fmac_f32_e32 v72, v73, v73
	v_add_f32_e32 v133, v72, v133
	ds_bpermute_b32 v134, v239, v130
	ds_bpermute_b32 v135, v239, v131
	ds_bpermute_b32 v136, v239, v132
	ds_bpermute_b32 v137, v239, v133
	s_waitcnt lgkmcnt(0)
	v_add_f32_e32 v130, v130, v134
	v_add_f32_e32 v131, v131, v135
	v_add_f32_e32 v132, v132, v136
	v_add_f32_e32 v133, v133, v137
	ds_bpermute_b32 v134, v240, v130
	ds_bpermute_b32 v135, v240, v131
	ds_bpermute_b32 v136, v240, v132
	ds_bpermute_b32 v137, v240, v133
	s_waitcnt lgkmcnt(0)
	v_add_f32_e32 v130, v130, v134
	v_add_f32_e32 v131, v131, v135
	v_add_f32_e32 v132, v132, v136
	v_add_f32_e32 v133, v133, v137
	ds_bpermute_b32 v134, v241, v130
	ds_bpermute_b32 v135, v241, v131
	ds_bpermute_b32 v136, v241, v132
	ds_bpermute_b32 v137, v241, v133
	s_waitcnt lgkmcnt(0)
	v_add_f32_e32 v130, v130, v134
	v_add_f32_e32 v131, v131, v135
	v_add_f32_e32 v132, v132, v136
	v_add_f32_e32 v133, v133, v137
	s_nop 3
	s_and_saveexec_b64 s[10:11], vcc
	global_store_dword v77, v130, s[44:45]
	global_store_dword v77, v131, s[44:45] offset:512
	global_store_dword v77, v132, s[44:45] offset:1024
	global_store_dword v77, v133, s[44:45] offset:1536
	s_or_b64 exec, exec, s[10:11]
	s_branch .Lkvs_done
